# adds the FFN up-projection k-loop rewritten by hand: 3-slot LDS ring, counted vmcnt, LDS-DMA issue interleaved with the MFMAs, own fp16 tile staging
# speedup vs baseline: 1.0160x; 1.0063x over previous
.LBB0_986:
	s_mul_hi_i32 s4, s52, 0x78787879
	s_lshr_b32 s5, s4, 31
	s_ashr_i32 s4, s4, 6
	s_add_i32 s53, s4, s5
	s_mul_i32 s4, s53, 0xffffff78
	s_add_i32 s4, s4, s52
	s_mulk_i32 s4, 0x7e
	s_add_i32 s54, s4, -2
	s_lshl_b32 s4, s53, 7
	s_ashr_i32 s5, s4, 31
	s_lshl_b64 s[34:35], s[4:5], 11
	s_add_u32 s12, s3, s34
	s_addc_u32 s13, s7, s35
	s_add_i32 s40, s4, 0xb00
	s_ashr_i32 s41, s40, 31
	v_add_u32_e32 v0, s54, v129
	s_lshl_b64 s[42:43], s[40:41], 11
	v_med3_i32 v0, v0, 0, v181
	v_readfirstlane_b32 s41, v169
	v_lshl_or_b32 v0, v0, 11, v182
	s_mov_b32 m0, s41
	v_readfirstlane_b32 s41, v184
	s_add_u32 s50, s3, s42
	v_add_u32_e32 v1, s54, v168
	global_load_lds_dwordx4 v0, s[14:15]
	s_mov_b32 m0, s41
	v_readfirstlane_b32 s41, v185
	s_addc_u32 s51, s7, s43
	v_med3_i32 v1, v1, 0, v181
	global_load_lds_dwordx4 v183, s[12:13]
	s_mov_b32 m0, s41
	v_readfirstlane_b32 s41, v186
	global_load_lds_dwordx4 v183, s[50:51]
	v_lshl_or_b32 v0, v1, 11, v182
	s_mov_b32 m0, s41
	v_readfirstlane_b32 s41, v188
	global_load_lds_dwordx4 v0, s[14:15]
	s_mov_b32 m0, s41
	v_lshl_add_u64 v[144:145], v[136:137], 0, s[34:35]
	global_load_lds_dwordx4 v187, s[12:13]
	v_readfirstlane_b32 s12, v189
	s_mov_b32 m0, s12
	s_mul_i32 s12, s53, 0x42f0
	global_load_lds_dwordx4 v187, s[50:51]
	v_subrev_u32_e32 v0, s12, v177
	v_med3_i32 v0, v0, 0, v181
	v_lshl_or_b32 v132, v0, 11, v182
	v_subrev_u32_e32 v0, s12, v178
	v_med3_i32 v0, v0, 0, v181
	v_lshl_add_u64 v[140:141], s[38:39], 0, v[132:133]
	v_lshl_or_b32 v132, v0, 11, v182
	v_lshl_add_u64 v[142:143], s[38:39], 0, v[132:133]
	v_lshl_add_u64 v[146:147], v[138:139], 0, s[34:35]
	v_lshl_add_u64 v[148:149], v[136:137], 0, s[42:43]
	v_lshl_add_u64 v[150:151], v[138:139], 0, s[42:43]
	v_add_u32_e32 v254, v170, v171
	v_readfirstlane_b32 s50, v169
	s_add_i32 s51, s50, 0x6000
	s_mov_b32 m0, s51
	s_nop 0
	global_load_lds_dwordx4 v[140:141], off
	v_lshl_add_u64 v[140:141], v[140:141], 0, 64
	s_add_i32 m0, s51, 0x2000
	s_nop 0
	global_load_lds_dwordx4 v[144:145], off
	v_lshl_add_u64 v[144:145], v[144:145], 0, 64
	s_add_i32 m0, s51, 0x4000
	s_nop 0
	global_load_lds_dwordx4 v[148:149], off
	v_lshl_add_u64 v[148:149], v[148:149], 0, 64
	s_add_i32 m0, s51, 0x400
	s_nop 0
	global_load_lds_dwordx4 v[142:143], off
	v_lshl_add_u64 v[142:143], v[142:143], 0, 64
	s_add_i32 m0, s51, 0x2400
	s_nop 0
	global_load_lds_dwordx4 v[146:147], off
	v_lshl_add_u64 v[146:147], v[146:147], 0, 64
	s_add_i32 m0, s51, 0x4400
	s_nop 0
	global_load_lds_dwordx4 v[150:151], off
	v_lshl_add_u64 v[150:151], v[150:151], 0, 64
	v_mov_b32_e32 v0, 0
	v_mov_b32_e32 v1, 0
	v_mov_b32_e32 v2, 0
	v_mov_b32_e32 v3, 0
	v_mov_b32_e32 v4, 0
	v_mov_b32_e32 v5, 0
	v_mov_b32_e32 v6, 0
	v_mov_b32_e32 v7, 0
	v_mov_b32_e32 v8, 0
	v_mov_b32_e32 v9, 0
	v_mov_b32_e32 v10, 0
	v_mov_b32_e32 v11, 0
	v_mov_b32_e32 v12, 0
	v_mov_b32_e32 v13, 0
	v_mov_b32_e32 v14, 0
	v_mov_b32_e32 v15, 0
	v_mov_b32_e32 v16, 0
	v_mov_b32_e32 v17, 0
	v_mov_b32_e32 v18, 0
	v_mov_b32_e32 v19, 0
	v_mov_b32_e32 v20, 0
	v_mov_b32_e32 v21, 0
	v_mov_b32_e32 v22, 0
	v_mov_b32_e32 v23, 0
	v_mov_b32_e32 v24, 0
	v_mov_b32_e32 v25, 0
	v_mov_b32_e32 v26, 0
	v_mov_b32_e32 v27, 0
	v_mov_b32_e32 v28, 0
	v_mov_b32_e32 v29, 0
	v_mov_b32_e32 v30, 0
	v_mov_b32_e32 v31, 0
	v_mov_b32_e32 v32, 0
	v_mov_b32_e32 v33, 0
	v_mov_b32_e32 v34, 0
	v_mov_b32_e32 v35, 0
	v_mov_b32_e32 v36, 0
	v_mov_b32_e32 v37, 0
	v_mov_b32_e32 v38, 0
	v_mov_b32_e32 v39, 0
	v_mov_b32_e32 v40, 0
	v_mov_b32_e32 v41, 0
	v_mov_b32_e32 v42, 0
	v_mov_b32_e32 v43, 0
	v_mov_b32_e32 v44, 0
	v_mov_b32_e32 v45, 0
	v_mov_b32_e32 v46, 0
	v_mov_b32_e32 v47, 0
	v_mov_b32_e32 v48, 0
	v_mov_b32_e32 v49, 0
	v_mov_b32_e32 v50, 0
	v_mov_b32_e32 v51, 0
	v_mov_b32_e32 v52, 0
	v_mov_b32_e32 v53, 0
	v_mov_b32_e32 v54, 0
	v_mov_b32_e32 v55, 0
	v_mov_b32_e32 v56, 0
	v_mov_b32_e32 v57, 0
	v_mov_b32_e32 v58, 0
	v_mov_b32_e32 v59, 0
	v_mov_b32_e32 v60, 0
	v_mov_b32_e32 v61, 0
	v_mov_b32_e32 v62, 0
	v_mov_b32_e32 v63, 0
	v_mov_b32_e32 v64, 0
	v_mov_b32_e32 v65, 0
	v_mov_b32_e32 v66, 0
	v_mov_b32_e32 v67, 0
	v_mov_b32_e32 v68, 0
	v_mov_b32_e32 v69, 0
	v_mov_b32_e32 v70, 0
	v_mov_b32_e32 v71, 0
	v_mov_b32_e32 v72, 0
	v_mov_b32_e32 v73, 0
	v_mov_b32_e32 v74, 0
	v_mov_b32_e32 v75, 0
	v_mov_b32_e32 v76, 0
	v_mov_b32_e32 v77, 0
	v_mov_b32_e32 v78, 0
	v_mov_b32_e32 v79, 0
	v_mov_b32_e32 v80, 0
	v_mov_b32_e32 v81, 0
	v_mov_b32_e32 v82, 0
	v_mov_b32_e32 v83, 0
	v_mov_b32_e32 v84, 0
	v_mov_b32_e32 v85, 0
	v_mov_b32_e32 v86, 0
	v_mov_b32_e32 v87, 0
	v_mov_b32_e32 v88, 0
	v_mov_b32_e32 v89, 0
	v_mov_b32_e32 v90, 0
	v_mov_b32_e32 v91, 0
	v_mov_b32_e32 v92, 0
	v_mov_b32_e32 v93, 0
	v_mov_b32_e32 v94, 0
	v_mov_b32_e32 v95, 0
	v_mov_b32_e32 v96, 0
	v_mov_b32_e32 v97, 0
	v_mov_b32_e32 v98, 0
	v_mov_b32_e32 v99, 0
	v_mov_b32_e32 v100, 0
	v_mov_b32_e32 v101, 0
	v_mov_b32_e32 v102, 0
	v_mov_b32_e32 v103, 0
	v_mov_b32_e32 v104, 0
	v_mov_b32_e32 v105, 0
	v_mov_b32_e32 v106, 0
	v_mov_b32_e32 v107, 0
	v_mov_b32_e32 v108, 0
	v_mov_b32_e32 v109, 0
	v_mov_b32_e32 v110, 0
	v_mov_b32_e32 v111, 0
	v_mov_b32_e32 v112, 0
	v_mov_b32_e32 v113, 0
	v_mov_b32_e32 v114, 0
	v_mov_b32_e32 v115, 0
	v_mov_b32_e32 v116, 0
	v_mov_b32_e32 v117, 0
	v_mov_b32_e32 v118, 0
	v_mov_b32_e32 v119, 0
	v_mov_b32_e32 v120, 0
	v_mov_b32_e32 v121, 0
	v_mov_b32_e32 v122, 0
	v_mov_b32_e32 v123, 0
	v_mov_b32_e32 v124, 0
	v_mov_b32_e32 v125, 0
	v_mov_b32_e32 v126, 0
	v_mov_b32_e32 v127, 0
	s_mov_b32 s13, 0
	s_mov_b32 s34, 0
	s_mov_b32 s35, 0xc000
.Lp8_loop:
	s_waitcnt vmcnt(6)
	s_barrier
	v_add_u32_e32 v252, s34, v254
	v_add_u32_e32 v253, s34, v172
	s_add_i32 s51, s50, s35
	ds_read_b128 v[190:193], v252
	ds_read_b128 v[194:197], v253 offset:8192
	ds_read_b128 v[206:209], v253 offset:16384
	ds_read_b128 v[202:205], v253 offset:9216
	ds_read_b128 v[210:213], v253 offset:17408
	ds_read_b128 v[214:217], v253 offset:10240
	ds_read_b128 v[222:225], v253 offset:18432
	ds_read_b128 v[218:221], v253 offset:11264
	ds_read_b128 v[226:229], v253 offset:19456
	ds_read_b128 v[198:201], v252 offset:1024
	s_mov_b32 m0, s51
	s_nop 0
	global_load_lds_dwordx4 v[140:141], off
	v_lshl_add_u64 v[140:141], v[140:141], 0, 64
	s_add_i32 m0, s51, 0x2000
	s_nop 0
	global_load_lds_dwordx4 v[144:145], off
	v_lshl_add_u64 v[144:145], v[144:145], 0, 64
	s_waitcnt lgkmcnt(8)
	v_mfma_f32_16x16x32_f16 v[120:123], v[190:193], v[194:197], v[120:123]
	s_waitcnt lgkmcnt(7)
	v_mfma_f32_16x16x32_f16 v[100:103], v[190:193], v[206:209], v[100:103]
	s_waitcnt lgkmcnt(6)
	v_mfma_f32_16x16x32_f16 v[124:127], v[190:193], v[202:205], v[124:127]
	s_add_i32 m0, s51, 0x4000
	s_waitcnt lgkmcnt(5)
	v_mfma_f32_16x16x32_f16 v[92:95], v[190:193], v[210:213], v[92:95]
	global_load_lds_dwordx4 v[148:149], off
	v_lshl_add_u64 v[148:149], v[148:149], 0, 64
	s_waitcnt lgkmcnt(4)
	v_mfma_f32_16x16x32_f16 v[116:119], v[190:193], v[214:217], v[116:119]
	s_waitcnt lgkmcnt(3)
	v_mfma_f32_16x16x32_f16 v[80:83], v[190:193], v[222:225], v[80:83]
	s_waitcnt lgkmcnt(2)
	v_mfma_f32_16x16x32_f16 v[112:115], v[190:193], v[218:221], v[112:115]
	s_waitcnt lgkmcnt(1)
	v_mfma_f32_16x16x32_f16 v[48:51], v[190:193], v[226:229], v[48:51]
	ds_read_b128 v[240:243], v252 offset:2048
	ds_read_b128 v[244:247], v252 offset:3072
	s_waitcnt lgkmcnt(2)
	v_mfma_f32_16x16x32_f16 v[108:111], v[198:201], v[194:197], v[108:111]
	v_mfma_f32_16x16x32_f16 v[40:43], v[198:201], v[206:209], v[40:43]
	v_mfma_f32_16x16x32_f16 v[104:107], v[198:201], v[202:205], v[104:107]
	s_add_i32 m0, s51, 0x400
	v_mfma_f32_16x16x32_f16 v[28:31], v[198:201], v[210:213], v[28:31]
	global_load_lds_dwordx4 v[142:143], off
	v_lshl_add_u64 v[142:143], v[142:143], 0, 64
	v_mfma_f32_16x16x32_f16 v[96:99], v[198:201], v[214:217], v[96:99]
	v_mfma_f32_16x16x32_f16 v[44:47], v[198:201], v[222:225], v[44:47]
	v_mfma_f32_16x16x32_f16 v[88:91], v[198:201], v[218:221], v[88:91]
	v_mfma_f32_16x16x32_f16 v[36:39], v[198:201], v[226:229], v[36:39]
	s_waitcnt lgkmcnt(1)
	v_mfma_f32_16x16x32_f16 v[84:87], v[240:243], v[194:197], v[84:87]
	v_mfma_f32_16x16x32_f16 v[32:35], v[240:243], v[206:209], v[32:35]
	v_mfma_f32_16x16x32_f16 v[76:79], v[240:243], v[202:205], v[76:79]
	s_add_i32 m0, s51, 0x2400
	v_mfma_f32_16x16x32_f16 v[24:27], v[240:243], v[210:213], v[24:27]
	global_load_lds_dwordx4 v[146:147], off
	v_lshl_add_u64 v[146:147], v[146:147], 0, 64
	v_mfma_f32_16x16x32_f16 v[72:75], v[240:243], v[214:217], v[72:75]
	v_mfma_f32_16x16x32_f16 v[20:23], v[240:243], v[222:225], v[20:23]
	v_mfma_f32_16x16x32_f16 v[68:71], v[240:243], v[218:221], v[68:71]
	v_mfma_f32_16x16x32_f16 v[16:19], v[240:243], v[226:229], v[16:19]
	s_waitcnt lgkmcnt(0)
	v_mfma_f32_16x16x32_f16 v[64:67], v[244:247], v[194:197], v[64:67]
	v_mfma_f32_16x16x32_f16 v[12:15], v[244:247], v[206:209], v[12:15]
	v_mfma_f32_16x16x32_f16 v[60:63], v[244:247], v[202:205], v[60:63]
	s_add_i32 m0, s51, 0x4400
	v_mfma_f32_16x16x32_f16 v[8:11], v[244:247], v[210:213], v[8:11]
	global_load_lds_dwordx4 v[150:151], off
	v_lshl_add_u64 v[150:151], v[150:151], 0, 64
	v_mfma_f32_16x16x32_f16 v[56:59], v[244:247], v[214:217], v[56:59]
	v_mfma_f32_16x16x32_f16 v[4:7], v[244:247], v[222:225], v[4:7]
	v_mfma_f32_16x16x32_f16 v[52:55], v[244:247], v[218:221], v[52:55]
	v_mfma_f32_16x16x32_f16 v[0:3], v[244:247], v[226:229], v[0:3]
	s_add_i32 s13, s13, 1
	s_add_i32 s34, s34, 0x6000
	s_cmp_eq_u32 s34, 0x12000
	s_cselect_b32 s34, 0, s34
	s_add_i32 s35, s35, 0x6000
	s_cmp_eq_u32 s35, 0x12000
	s_cselect_b32 s35, 0, s35
	s_cmp_lt_u32 s13, 30
	s_cbranch_scc1 .Lp8_loop
	s_waitcnt vmcnt(6)
	s_barrier
	v_add_u32_e32 v252, s34, v254
	v_add_u32_e32 v253, s34, v172
	ds_read_b128 v[190:193], v252
	ds_read_b128 v[194:197], v253 offset:8192
	ds_read_b128 v[206:209], v253 offset:16384
	ds_read_b128 v[202:205], v253 offset:9216
	ds_read_b128 v[210:213], v253 offset:17408
	ds_read_b128 v[214:217], v253 offset:10240
	ds_read_b128 v[222:225], v253 offset:18432
	ds_read_b128 v[218:221], v253 offset:11264
	ds_read_b128 v[226:229], v253 offset:19456
	ds_read_b128 v[198:201], v252 offset:1024
	s_waitcnt lgkmcnt(8)
	v_mfma_f32_16x16x32_f16 v[120:123], v[190:193], v[194:197], v[120:123]
	s_waitcnt lgkmcnt(7)
	v_mfma_f32_16x16x32_f16 v[100:103], v[190:193], v[206:209], v[100:103]
	s_waitcnt lgkmcnt(6)
	v_mfma_f32_16x16x32_f16 v[124:127], v[190:193], v[202:205], v[124:127]
	s_waitcnt lgkmcnt(5)
	v_mfma_f32_16x16x32_f16 v[92:95], v[190:193], v[210:213], v[92:95]
	s_waitcnt lgkmcnt(4)
	v_mfma_f32_16x16x32_f16 v[116:119], v[190:193], v[214:217], v[116:119]
	s_waitcnt lgkmcnt(3)
	v_mfma_f32_16x16x32_f16 v[80:83], v[190:193], v[222:225], v[80:83]
	s_waitcnt lgkmcnt(2)
	v_mfma_f32_16x16x32_f16 v[112:115], v[190:193], v[218:221], v[112:115]
	s_waitcnt lgkmcnt(1)
	v_mfma_f32_16x16x32_f16 v[48:51], v[190:193], v[226:229], v[48:51]
	ds_read_b128 v[240:243], v252 offset:2048
	ds_read_b128 v[244:247], v252 offset:3072
	s_waitcnt lgkmcnt(2)
	v_mfma_f32_16x16x32_f16 v[108:111], v[198:201], v[194:197], v[108:111]
	v_mfma_f32_16x16x32_f16 v[40:43], v[198:201], v[206:209], v[40:43]
	v_mfma_f32_16x16x32_f16 v[104:107], v[198:201], v[202:205], v[104:107]
	v_mfma_f32_16x16x32_f16 v[28:31], v[198:201], v[210:213], v[28:31]
	v_mfma_f32_16x16x32_f16 v[96:99], v[198:201], v[214:217], v[96:99]
	v_mfma_f32_16x16x32_f16 v[44:47], v[198:201], v[222:225], v[44:47]
	v_mfma_f32_16x16x32_f16 v[88:91], v[198:201], v[218:221], v[88:91]
	v_mfma_f32_16x16x32_f16 v[36:39], v[198:201], v[226:229], v[36:39]
	s_waitcnt lgkmcnt(1)
	v_mfma_f32_16x16x32_f16 v[84:87], v[240:243], v[194:197], v[84:87]
	v_mfma_f32_16x16x32_f16 v[32:35], v[240:243], v[206:209], v[32:35]
	v_mfma_f32_16x16x32_f16 v[76:79], v[240:243], v[202:205], v[76:79]
	v_mfma_f32_16x16x32_f16 v[24:27], v[240:243], v[210:213], v[24:27]
	v_mfma_f32_16x16x32_f16 v[72:75], v[240:243], v[214:217], v[72:75]
	v_mfma_f32_16x16x32_f16 v[20:23], v[240:243], v[222:225], v[20:23]
	v_mfma_f32_16x16x32_f16 v[68:71], v[240:243], v[218:221], v[68:71]
	v_mfma_f32_16x16x32_f16 v[16:19], v[240:243], v[226:229], v[16:19]
	s_waitcnt lgkmcnt(0)
	v_mfma_f32_16x16x32_f16 v[64:67], v[244:247], v[194:197], v[64:67]
	v_mfma_f32_16x16x32_f16 v[12:15], v[244:247], v[206:209], v[12:15]
	v_mfma_f32_16x16x32_f16 v[60:63], v[244:247], v[202:205], v[60:63]
	v_mfma_f32_16x16x32_f16 v[8:11], v[244:247], v[210:213], v[8:11]
	v_mfma_f32_16x16x32_f16 v[56:59], v[244:247], v[214:217], v[56:59]
	v_mfma_f32_16x16x32_f16 v[4:7], v[244:247], v[222:225], v[4:7]
	v_mfma_f32_16x16x32_f16 v[52:55], v[244:247], v[218:221], v[52:55]
	v_mfma_f32_16x16x32_f16 v[0:3], v[244:247], v[226:229], v[0:3]
	s_add_i32 s34, s34, 0x6000
	s_cmp_eq_u32 s34, 0x12000
	s_cselect_b32 s34, 0, s34
	s_waitcnt vmcnt(0)
	s_barrier
	v_add_u32_e32 v252, s34, v254
	v_add_u32_e32 v253, s34, v172
	ds_read_b128 v[190:193], v252
	ds_read_b128 v[194:197], v253 offset:8192
	ds_read_b128 v[206:209], v253 offset:16384
	ds_read_b128 v[202:205], v253 offset:9216
	ds_read_b128 v[210:213], v253 offset:17408
	ds_read_b128 v[214:217], v253 offset:10240
	ds_read_b128 v[222:225], v253 offset:18432
	ds_read_b128 v[218:221], v253 offset:11264
	ds_read_b128 v[226:229], v253 offset:19456
	ds_read_b128 v[198:201], v252 offset:1024
	s_waitcnt lgkmcnt(8)
	v_mfma_f32_16x16x32_f16 v[120:123], v[190:193], v[194:197], v[120:123]
	s_waitcnt lgkmcnt(7)
	v_mfma_f32_16x16x32_f16 v[100:103], v[190:193], v[206:209], v[100:103]
	s_waitcnt lgkmcnt(6)
	v_mfma_f32_16x16x32_f16 v[124:127], v[190:193], v[202:205], v[124:127]
	s_waitcnt lgkmcnt(5)
	v_mfma_f32_16x16x32_f16 v[92:95], v[190:193], v[210:213], v[92:95]
	s_waitcnt lgkmcnt(4)
	v_mfma_f32_16x16x32_f16 v[116:119], v[190:193], v[214:217], v[116:119]
	s_waitcnt lgkmcnt(3)
	v_mfma_f32_16x16x32_f16 v[80:83], v[190:193], v[222:225], v[80:83]
	s_waitcnt lgkmcnt(2)
	v_mfma_f32_16x16x32_f16 v[112:115], v[190:193], v[218:221], v[112:115]
	s_waitcnt lgkmcnt(1)
	v_mfma_f32_16x16x32_f16 v[48:51], v[190:193], v[226:229], v[48:51]
	ds_read_b128 v[240:243], v252 offset:2048
	ds_read_b128 v[244:247], v252 offset:3072
	s_waitcnt lgkmcnt(2)
	v_mfma_f32_16x16x32_f16 v[108:111], v[198:201], v[194:197], v[108:111]
	v_mfma_f32_16x16x32_f16 v[40:43], v[198:201], v[206:209], v[40:43]
	v_mfma_f32_16x16x32_f16 v[104:107], v[198:201], v[202:205], v[104:107]
	v_mfma_f32_16x16x32_f16 v[28:31], v[198:201], v[210:213], v[28:31]
	v_mfma_f32_16x16x32_f16 v[96:99], v[198:201], v[214:217], v[96:99]
	v_mfma_f32_16x16x32_f16 v[44:47], v[198:201], v[222:225], v[44:47]
	v_mfma_f32_16x16x32_f16 v[88:91], v[198:201], v[218:221], v[88:91]
	v_mfma_f32_16x16x32_f16 v[36:39], v[198:201], v[226:229], v[36:39]
	s_waitcnt lgkmcnt(1)
	v_mfma_f32_16x16x32_f16 v[84:87], v[240:243], v[194:197], v[84:87]
	v_mfma_f32_16x16x32_f16 v[32:35], v[240:243], v[206:209], v[32:35]
	v_mfma_f32_16x16x32_f16 v[76:79], v[240:243], v[202:205], v[76:79]
	v_mfma_f32_16x16x32_f16 v[24:27], v[240:243], v[210:213], v[24:27]
	v_mfma_f32_16x16x32_f16 v[72:75], v[240:243], v[214:217], v[72:75]
	v_mfma_f32_16x16x32_f16 v[20:23], v[240:243], v[222:225], v[20:23]
	v_mfma_f32_16x16x32_f16 v[68:71], v[240:243], v[218:221], v[68:71]
	v_mfma_f32_16x16x32_f16 v[16:19], v[240:243], v[226:229], v[16:19]
	s_waitcnt lgkmcnt(0)
	v_mfma_f32_16x16x32_f16 v[64:67], v[244:247], v[194:197], v[64:67]
	v_mfma_f32_16x16x32_f16 v[12:15], v[244:247], v[206:209], v[12:15]
	v_mfma_f32_16x16x32_f16 v[60:63], v[244:247], v[202:205], v[60:63]
	v_mfma_f32_16x16x32_f16 v[8:11], v[244:247], v[210:213], v[8:11]
	v_mfma_f32_16x16x32_f16 v[56:59], v[244:247], v[214:217], v[56:59]
	v_mfma_f32_16x16x32_f16 v[4:7], v[244:247], v[222:225], v[4:7]
	v_mfma_f32_16x16x32_f16 v[52:55], v[244:247], v[218:221], v[52:55]
	v_mfma_f32_16x16x32_f16 v[0:3], v[244:247], v[226:229], v[0:3]
	s_nop 7
	s_barrier
	v_lshrrev_b32_e32 v240, 1, v154
	v_and_b32_e32 v241, 1, v154
	v_lshlrev_b32_e32 v240, 14, v240
	v_lshrrev_b32_e32 v242, 4, v152
	v_lshl_or_b32 v240, v241, 7, v240
	v_and_b32_e32 v241, 15, v152
	v_lshl_or_b32 v240, v242, 10, v240
	s_nop 0
	v_lshl_or_b32 v240, v241, 1, v240
	v_cvt_f16_f32_e32 v120, v120
	v_cvt_f16_f32_e32 v121, v121
	v_cvt_f16_f32_e32 v122, v122
	v_cvt_f16_f32_e32 v123, v123
	ds_write_b16 v240, v120 offset:0
	ds_write_b16 v240, v121 offset:256
	ds_write_b16 v240, v122 offset:512
	ds_write_b16 v240, v123 offset:768
	v_cvt_f16_f32_e32 v124, v124
	v_cvt_f16_f32_e32 v125, v125
	v_cvt_f16_f32_e32 v126, v126
	v_cvt_f16_f32_e32 v127, v127
	ds_write_b16 v240, v124 offset:32
	ds_write_b16 v240, v125 offset:288
	ds_write_b16 v240, v126 offset:544
	ds_write_b16 v240, v127 offset:800
	v_cvt_f16_f32_e32 v116, v116
	v_cvt_f16_f32_e32 v117, v117
	v_cvt_f16_f32_e32 v118, v118
	v_cvt_f16_f32_e32 v119, v119
	ds_write_b16 v240, v116 offset:64
	ds_write_b16 v240, v117 offset:320
	ds_write_b16 v240, v118 offset:576
	ds_write_b16 v240, v119 offset:832
	v_cvt_f16_f32_e32 v112, v112
	v_cvt_f16_f32_e32 v113, v113
	v_cvt_f16_f32_e32 v114, v114
	v_cvt_f16_f32_e32 v115, v115
	ds_write_b16 v240, v112 offset:96
	ds_write_b16 v240, v113 offset:352
	ds_write_b16 v240, v114 offset:608
	ds_write_b16 v240, v115 offset:864
	v_cvt_f16_f32_e32 v108, v108
	v_cvt_f16_f32_e32 v109, v109
	v_cvt_f16_f32_e32 v110, v110
	v_cvt_f16_f32_e32 v111, v111
	ds_write_b16 v240, v108 offset:4096
	ds_write_b16 v240, v109 offset:4352
	ds_write_b16 v240, v110 offset:4608
	ds_write_b16 v240, v111 offset:4864
	v_cvt_f16_f32_e32 v104, v104
	v_cvt_f16_f32_e32 v105, v105
	v_cvt_f16_f32_e32 v106, v106
	v_cvt_f16_f32_e32 v107, v107
	ds_write_b16 v240, v104 offset:4128
	ds_write_b16 v240, v105 offset:4384
	ds_write_b16 v240, v106 offset:4640
	ds_write_b16 v240, v107 offset:4896
	v_cvt_f16_f32_e32 v96, v96
	v_cvt_f16_f32_e32 v97, v97
	v_cvt_f16_f32_e32 v98, v98
	v_cvt_f16_f32_e32 v99, v99
	ds_write_b16 v240, v96 offset:4160
	ds_write_b16 v240, v97 offset:4416
	ds_write_b16 v240, v98 offset:4672
	ds_write_b16 v240, v99 offset:4928
	v_cvt_f16_f32_e32 v88, v88
	v_cvt_f16_f32_e32 v89, v89
	v_cvt_f16_f32_e32 v90, v90
	v_cvt_f16_f32_e32 v91, v91
	ds_write_b16 v240, v88 offset:4192
	ds_write_b16 v240, v89 offset:4448
	ds_write_b16 v240, v90 offset:4704
	ds_write_b16 v240, v91 offset:4960
	v_cvt_f16_f32_e32 v84, v84
	v_cvt_f16_f32_e32 v85, v85
	v_cvt_f16_f32_e32 v86, v86
	v_cvt_f16_f32_e32 v87, v87
	ds_write_b16 v240, v84 offset:8192
	ds_write_b16 v240, v85 offset:8448
	ds_write_b16 v240, v86 offset:8704
	ds_write_b16 v240, v87 offset:8960
	v_cvt_f16_f32_e32 v76, v76
	v_cvt_f16_f32_e32 v77, v77
	v_cvt_f16_f32_e32 v78, v78
	v_cvt_f16_f32_e32 v79, v79
	ds_write_b16 v240, v76 offset:8224
	ds_write_b16 v240, v77 offset:8480
	ds_write_b16 v240, v78 offset:8736
	ds_write_b16 v240, v79 offset:8992
	v_cvt_f16_f32_e32 v72, v72
	v_cvt_f16_f32_e32 v73, v73
	v_cvt_f16_f32_e32 v74, v74
	v_cvt_f16_f32_e32 v75, v75
	ds_write_b16 v240, v72 offset:8256
	ds_write_b16 v240, v73 offset:8512
	ds_write_b16 v240, v74 offset:8768
	ds_write_b16 v240, v75 offset:9024
	v_cvt_f16_f32_e32 v68, v68
	v_cvt_f16_f32_e32 v69, v69
	v_cvt_f16_f32_e32 v70, v70
	v_cvt_f16_f32_e32 v71, v71
	ds_write_b16 v240, v68 offset:8288
	ds_write_b16 v240, v69 offset:8544
	ds_write_b16 v240, v70 offset:8800
	ds_write_b16 v240, v71 offset:9056
	v_cvt_f16_f32_e32 v64, v64
	v_cvt_f16_f32_e32 v65, v65
	v_cvt_f16_f32_e32 v66, v66
	v_cvt_f16_f32_e32 v67, v67
	ds_write_b16 v240, v64 offset:12288
	ds_write_b16 v240, v65 offset:12544
	ds_write_b16 v240, v66 offset:12800
	ds_write_b16 v240, v67 offset:13056
	v_cvt_f16_f32_e32 v60, v60
	v_cvt_f16_f32_e32 v61, v61
	v_cvt_f16_f32_e32 v62, v62
	v_cvt_f16_f32_e32 v63, v63
	ds_write_b16 v240, v60 offset:12320
	ds_write_b16 v240, v61 offset:12576
	ds_write_b16 v240, v62 offset:12832
	ds_write_b16 v240, v63 offset:13088
	v_cvt_f16_f32_e32 v56, v56
	v_cvt_f16_f32_e32 v57, v57
	v_cvt_f16_f32_e32 v58, v58
	v_cvt_f16_f32_e32 v59, v59
	ds_write_b16 v240, v56 offset:12352
	ds_write_b16 v240, v57 offset:12608
	ds_write_b16 v240, v58 offset:12864
	ds_write_b16 v240, v59 offset:13120
	v_cvt_f16_f32_e32 v52, v52
	v_cvt_f16_f32_e32 v53, v53
	v_cvt_f16_f32_e32 v54, v54
	v_cvt_f16_f32_e32 v55, v55
	ds_write_b16 v240, v52 offset:12384
	ds_write_b16 v240, v53 offset:12640
	ds_write_b16 v240, v54 offset:12896
	ds_write_b16 v240, v55 offset:13152
	v_cvt_f16_f32_e32 v100, v100
	v_cvt_f16_f32_e32 v101, v101
	v_cvt_f16_f32_e32 v102, v102
	v_cvt_f16_f32_e32 v103, v103
	ds_write_b16 v240, v100 offset:32768
	ds_write_b16 v240, v101 offset:33024
	ds_write_b16 v240, v102 offset:33280
	ds_write_b16 v240, v103 offset:33536
	v_cvt_f16_f32_e32 v92, v92
	v_cvt_f16_f32_e32 v93, v93
	v_cvt_f16_f32_e32 v94, v94
	v_cvt_f16_f32_e32 v95, v95
	ds_write_b16 v240, v92 offset:32800
	ds_write_b16 v240, v93 offset:33056
	ds_write_b16 v240, v94 offset:33312
	ds_write_b16 v240, v95 offset:33568
	v_cvt_f16_f32_e32 v80, v80
	v_cvt_f16_f32_e32 v81, v81
	v_cvt_f16_f32_e32 v82, v82
	v_cvt_f16_f32_e32 v83, v83
	ds_write_b16 v240, v80 offset:32832
	ds_write_b16 v240, v81 offset:33088
	ds_write_b16 v240, v82 offset:33344
	ds_write_b16 v240, v83 offset:33600
	v_cvt_f16_f32_e32 v48, v48
	v_cvt_f16_f32_e32 v49, v49
	v_cvt_f16_f32_e32 v50, v50
	v_cvt_f16_f32_e32 v51, v51
	ds_write_b16 v240, v48 offset:32864
	ds_write_b16 v240, v49 offset:33120
	ds_write_b16 v240, v50 offset:33376
	ds_write_b16 v240, v51 offset:33632
	v_cvt_f16_f32_e32 v40, v40
	v_cvt_f16_f32_e32 v41, v41
	v_cvt_f16_f32_e32 v42, v42
	v_cvt_f16_f32_e32 v43, v43
	ds_write_b16 v240, v40 offset:36864
	ds_write_b16 v240, v41 offset:37120
	ds_write_b16 v240, v42 offset:37376
	ds_write_b16 v240, v43 offset:37632
	v_cvt_f16_f32_e32 v28, v28
	v_cvt_f16_f32_e32 v29, v29
	v_cvt_f16_f32_e32 v30, v30
	v_cvt_f16_f32_e32 v31, v31
	ds_write_b16 v240, v28 offset:36896
	ds_write_b16 v240, v29 offset:37152
	ds_write_b16 v240, v30 offset:37408
	ds_write_b16 v240, v31 offset:37664
	v_cvt_f16_f32_e32 v44, v44
	v_cvt_f16_f32_e32 v45, v45
	v_cvt_f16_f32_e32 v46, v46
	v_cvt_f16_f32_e32 v47, v47
	ds_write_b16 v240, v44 offset:36928
	ds_write_b16 v240, v45 offset:37184
	ds_write_b16 v240, v46 offset:37440
	ds_write_b16 v240, v47 offset:37696
	v_cvt_f16_f32_e32 v36, v36
	v_cvt_f16_f32_e32 v37, v37
	v_cvt_f16_f32_e32 v38, v38
	v_cvt_f16_f32_e32 v39, v39
	ds_write_b16 v240, v36 offset:36960
	ds_write_b16 v240, v37 offset:37216
	ds_write_b16 v240, v38 offset:37472
	ds_write_b16 v240, v39 offset:37728
	v_cvt_f16_f32_e32 v32, v32
	v_cvt_f16_f32_e32 v33, v33
	v_cvt_f16_f32_e32 v34, v34
	v_cvt_f16_f32_e32 v35, v35
	ds_write_b16 v240, v32 offset:40960
	ds_write_b16 v240, v33 offset:41216
	ds_write_b16 v240, v34 offset:41472
	ds_write_b16 v240, v35 offset:41728
	v_cvt_f16_f32_e32 v24, v24
	v_cvt_f16_f32_e32 v25, v25
	v_cvt_f16_f32_e32 v26, v26
	v_cvt_f16_f32_e32 v27, v27
	ds_write_b16 v240, v24 offset:40992
	ds_write_b16 v240, v25 offset:41248
	ds_write_b16 v240, v26 offset:41504
	ds_write_b16 v240, v27 offset:41760
	v_cvt_f16_f32_e32 v20, v20
	v_cvt_f16_f32_e32 v21, v21
	v_cvt_f16_f32_e32 v22, v22
	v_cvt_f16_f32_e32 v23, v23
	ds_write_b16 v240, v20 offset:41024
	ds_write_b16 v240, v21 offset:41280
	ds_write_b16 v240, v22 offset:41536
	ds_write_b16 v240, v23 offset:41792
	v_cvt_f16_f32_e32 v16, v16
	v_cvt_f16_f32_e32 v17, v17
	v_cvt_f16_f32_e32 v18, v18
	v_cvt_f16_f32_e32 v19, v19
	ds_write_b16 v240, v16 offset:41056
	ds_write_b16 v240, v17 offset:41312
	ds_write_b16 v240, v18 offset:41568
	ds_write_b16 v240, v19 offset:41824
	v_cvt_f16_f32_e32 v12, v12
	v_cvt_f16_f32_e32 v13, v13
	v_cvt_f16_f32_e32 v14, v14
	v_cvt_f16_f32_e32 v15, v15
	ds_write_b16 v240, v12 offset:45056
	ds_write_b16 v240, v13 offset:45312
	ds_write_b16 v240, v14 offset:45568
	ds_write_b16 v240, v15 offset:45824
	v_cvt_f16_f32_e32 v8, v8
	v_cvt_f16_f32_e32 v9, v9
	v_cvt_f16_f32_e32 v10, v10
	v_cvt_f16_f32_e32 v11, v11
	ds_write_b16 v240, v8 offset:45088
	ds_write_b16 v240, v9 offset:45344
	ds_write_b16 v240, v10 offset:45600
	ds_write_b16 v240, v11 offset:45856
	v_cvt_f16_f32_e32 v4, v4
	v_cvt_f16_f32_e32 v5, v5
	v_cvt_f16_f32_e32 v6, v6
	v_cvt_f16_f32_e32 v7, v7
	ds_write_b16 v240, v4 offset:45120
	ds_write_b16 v240, v5 offset:45376
	ds_write_b16 v240, v6 offset:45632
	ds_write_b16 v240, v7 offset:45888
	v_cvt_f16_f32_e32 v0, v0
	v_cvt_f16_f32_e32 v1, v1
	v_cvt_f16_f32_e32 v2, v2
	v_cvt_f16_f32_e32 v3, v3
	ds_write_b16 v240, v0 offset:45152
	ds_write_b16 v240, v1 offset:45408
	ds_write_b16 v240, v2 offset:45664
	ds_write_b16 v240, v3 offset:45920
	v_or_b32_e32 v48, s4, v128
	v_or_b32_e32 v50, s40, v128
	v_ashrrev_i32_e32 v49, 31, v48
	v_ashrrev_i32_e32 v51, 31, v50
	v_lshlrev_b64 v[16:17], 2, v[48:49]
	v_lshlrev_b64 v[40:41], 2, v[50:51]
	v_lshl_add_u64 v[4:5], s[22:23], 0, v[16:17]
	v_lshl_add_u64 v[12:13], s[20:21], 0, v[16:17]
	v_lshl_add_u64 v[20:21], s[24:25], 0, v[16:17]
	v_lshl_add_u64 v[28:29], s[22:23], 0, v[40:41]
	v_lshl_add_u64 v[36:37], s[20:21], 0, v[40:41]
	v_lshl_add_u64 v[44:45], s[24:25], 0, v[40:41]
	s_waitcnt lgkmcnt(0)
	s_barrier
	global_load_dwordx4 v[0:3], v[4:5], off offset:16
	s_nop 0
	global_load_dwordx4 v[4:7], v[4:5], off
	s_nop 0
	global_load_dwordx4 v[8:11], v[12:13], off
	s_nop 0
	global_load_dwordx4 v[12:15], v[12:13], off offset:16
	s_nop 0
	global_load_dwordx4 v[16:19], v[20:21], off
	s_nop 0
	global_load_dwordx4 v[20:23], v[20:21], off offset:16
	s_nop 0
	global_load_dwordx4 v[24:27], v[28:29], off offset:16
	s_nop 0
	global_load_dwordx4 v[28:31], v[28:29], off
	s_nop 0
	global_load_dwordx4 v[32:35], v[36:37], off offset:16
	s_nop 0
	global_load_dwordx4 v[36:39], v[36:37], off
	s_nop 0
	global_load_dwordx4 v[40:43], v[44:45], off offset:16
	s_nop 0
	global_load_dwordx4 v[44:47], v[44:45], off
	v_lshl_add_u64 v[52:53], s[4:5], 1, v[134:135]
	v_subrev_u32_e32 v56, s12, v180
	s_mov_b32 s53, 0
	v_mov_b32_e32 v57, v179
	s_waitcnt vmcnt(11)
	v_cvt_pk_f16_f32 v3, v2, v3
	v_cvt_pk_f16_f32 v2, v0, v1
	s_waitcnt vmcnt(10)
	v_cvt_pk_f16_f32 v1, v6, v7
	v_cvt_pk_f16_f32 v0, v4, v5
	s_waitcnt vmcnt(8)
	v_cvt_pk_f16_f32 v5, v14, v15
	v_cvt_pk_f16_f32 v4, v12, v13
	v_cvt_pk_f16_f32 v7, v10, v11
	v_cvt_pk_f16_f32 v6, v8, v9
	s_waitcnt vmcnt(6)
	v_cvt_pk_f16_f32 v9, v22, v23
	v_cvt_pk_f16_f32 v8, v20, v21
	v_cvt_pk_f16_f32 v11, v18, v19
	v_cvt_pk_f16_f32 v10, v16, v17
	s_waitcnt vmcnt(5)
	v_cvt_pk_f16_f32 v13, v26, v27
	v_cvt_pk_f16_f32 v12, v24, v25
	s_waitcnt vmcnt(4)
	v_cvt_pk_f16_f32 v15, v30, v31
	v_cvt_pk_f16_f32 v14, v28, v29
	s_waitcnt vmcnt(3)
	v_cvt_pk_f16_f32 v17, v34, v35
	v_cvt_pk_f16_f32 v16, v32, v33
	s_waitcnt vmcnt(2)
	v_cvt_pk_f16_f32 v19, v38, v39
	v_cvt_pk_f16_f32 v18, v36, v37
	s_waitcnt vmcnt(1)
	v_cvt_pk_f16_f32 v21, v42, v43
	v_cvt_pk_f16_f32 v20, v40, v41
	s_waitcnt vmcnt(0)
	v_cvt_pk_f16_f32 v23, v46, v47
	v_cvt_pk_f16_f32 v22, v44, v45
	s_branch .LBB0_990

	.amdhsa_kernel _Z4mega6Params
		.amdhsa_group_segment_fixed_size 77840
		.amdhsa_private_segment_fixed_size 0
		.amdhsa_kernarg_size 520
		.amdhsa_user_sgpr_count 2
		.amdhsa_user_sgpr_dispatch_ptr 0
		.amdhsa_user_sgpr_queue_ptr 0
		.amdhsa_user_sgpr_kernarg_segment_ptr 1
		.amdhsa_user_sgpr_dispatch_id 0
		.amdhsa_user_sgpr_kernarg_preload_length 0
		.amdhsa_user_sgpr_kernarg_preload_offset 0
		.amdhsa_user_sgpr_private_segment_size 0
		.amdhsa_uses_dynamic_stack 0
		.amdhsa_enable_private_segment 0
		.amdhsa_system_sgpr_workgroup_id_x 1
		.amdhsa_system_sgpr_workgroup_id_y 0
		.amdhsa_system_sgpr_workgroup_id_z 0
		.amdhsa_system_sgpr_workgroup_info 0
		.amdhsa_system_vgpr_workitem_id 2
		.amdhsa_next_free_vgpr 256
		.amdhsa_next_free_sgpr 98
		.amdhsa_accum_offset 256
		.amdhsa_reserve_vcc 1
		.amdhsa_float_round_mode_32 0
		.amdhsa_float_round_mode_16_64 0
		.amdhsa_float_denorm_mode_32 3
		.amdhsa_float_denorm_mode_16_64 3
		.amdhsa_dx10_clamp 1
		.amdhsa_ieee_mode 1
		.amdhsa_fp16_overflow 0
		.amdhsa_tg_split 0
		.amdhsa_exception_fp_ieee_invalid_op 0
		.amdhsa_exception_fp_denorm_src 0
		.amdhsa_exception_fp_ieee_div_zero 0
		.amdhsa_exception_fp_ieee_overflow 0
		.amdhsa_exception_fp_ieee_underflow 0
		.amdhsa_exception_fp_ieee_inexact 0
		.amdhsa_exception_int_div_zero 0
	.end_amdhsa_kernel

amdhsa.kernels:
  - .agpr_count:     0
    .args:
      - .offset:         0
        .size:           264
        .value_kind:     by_value
      - .offset:         264
        .size:           4
        .value_kind:     hidden_block_count_x
      - .offset:         268
        .size:           4
        .value_kind:     hidden_block_count_y
      - .offset:         272
        .size:           4
        .value_kind:     hidden_block_count_z
      - .offset:         276
        .size:           2
        .value_kind:     hidden_group_size_x
      - .offset:         278
        .size:           2
        .value_kind:     hidden_group_size_y
      - .offset:         280
        .size:           2
        .value_kind:     hidden_group_size_z
      - .offset:         282
        .size:           2
        .value_kind:     hidden_remainder_x
      - .offset:         284
        .size:           2
        .value_kind:     hidden_remainder_y
      - .offset:         286
        .size:           2
        .value_kind:     hidden_remainder_z
      - .offset:         304
        .size:           8
        .value_kind:     hidden_global_offset_x
      - .offset:         312
        .size:           8
        .value_kind:     hidden_global_offset_y
      - .offset:         320
        .size:           8
        .value_kind:     hidden_global_offset_z
      - .offset:         328
        .size:           2
        .value_kind:     hidden_grid_dims
      - .offset:         352
        .size:           8
        .value_kind:     hidden_multigrid_sync_arg
    .group_segment_fixed_size: 77840
    .kernarg_segment_align: 8
    .kernarg_segment_size: 520
    .language:       OpenCL C
    .language_version:
      - 2
      - 0
    .max_flat_workgroup_size: 256
    .name:           _Z4mega6Params
    .private_segment_fixed_size: 0
    .sgpr_count:     104
    .sgpr_spill_count: 44
    .symbol:         _Z4mega6Params.kd
    .uniform_work_group_size: 1
    .uses_dynamic_stack: false
    .vgpr_count:     256
    .vgpr_spill_count: 0
    .wavefront_size: 64
